# inproj B-layer table conversion done only by the 200 blocks without a 4th tile (guard R<=5/8 grid)
# speedup vs baseline: 1.0086x; 1.0086x over previous
.Lmodd_ip:
	s_lshr_b32 s31, s2, 3
	s_mul_i32 s31, s31, 5
	s_cmp_gt_u32 s30, s31
	s_cselect_b32 s30, 0, s30
	s_sub_u32 s2, s2, s30
	s_cmp_lt_u32 s8, s30
	s_cbranch_scc1 .LBB0_730
	s_sub_u32 s8, s8, s30
	v_readlane_b32 s1, v249, 31
	v_writelane_b32 v249, s2, 19
	s_load_dwordx2 s[0:1], s[0:1], 0x160
	s_ashr_i32 s9, s8, 31
	v_writelane_b32 v249, s3, 20
	s_lshl_b64 s[2:3], s[2:3], 8
	s_lshl_b64 s[4:5], s[8:9], 8
	v_readlane_b32 s6, v249, 41
	v_readlane_b32 s7, v249, 42
	s_add_u32 s10, s4, s6
	v_mov_b32_e32 v0, v220
	s_addc_u32 s11, s5, s7
	v_readlane_b32 s14, v249, 43
	v_ashrrev_i32_e32 v1, 31, v0
	v_lshl_add_u64 v[76:77], s[10:11], 0, v[0:1]
	v_readlane_b32 s15, v249, 44
	s_nop 1
	v_cmp_gt_u64_e32 vcc, s[14:15], v[76:77]
	s_and_saveexec_b64 s[4:5], vcc
	s_cbranch_execz .LBB0_722
	v_readlane_b32 s12, v249, 37
	v_readlane_b32 s13, v249, 38
	v_and_b32_e32 v2, 31, v0
	s_lshl_b64 s[12:13], s[12:13], 26
	s_lshl_b64 s[8:9], s[8:9], 15
	v_mul_u32_u24_e32 v2, 24, v2
	v_mov_b32_e32 v3, v80
	s_add_u32 s8, s12, s8
	s_waitcnt lgkmcnt(0)
	v_lshl_add_u64 v[68:69], s[0:1], 0, v[2:3]
	s_addc_u32 s9, s13, s9
	v_lshlrev_b64 v[2:3], 7, v[0:1]
	v_readlane_b32 s6, v249, 30
	v_lshl_add_u64 v[70:71], s[8:9], 0, v[2:3]
	v_readlane_b32 s8, v249, 19
	v_readlane_b32 s7, v249, 31
	v_readlane_b32 s9, v249, 20
	s_load_dwordx2 s[6:7], s[6:7], 0xb8
	s_lshl_b64 s[8:9], s[8:9], 16
	s_add_u32 s10, s10, s2
	s_addc_u32 s11, s11, s3
	v_lshl_add_u64 v[0:1], s[10:11], 0, v[0:1]
	s_waitcnt vmcnt(0)
	v_lshlrev_b64 v[72:73], 7, v[0:1]
	s_mov_b64 s[10:11], 0
	s_branch .LBB0_718
